# speedup vs baseline: 1.0082x; 1.0082x over previous
.LBB0_793:
	s_or_b64 exec, exec, s[0:1]
	v_readlane_b32 s0, v252, 48
	s_add_u32 s10, s60, 0x11000000
	v_readlane_b32 s1, v252, 49
	s_addc_u32 s11, s61, 0
	s_and_b64 vcc, exec, s[0:1]
	s_waitcnt lgkmcnt(0)
	s_barrier
	s_cbranch_vccz .LBB0_842
	v_mov_b32_e32 v140, v218
	s_mov_b32 s0, 0
	s_cmp_gt_i32 s0, 0
	v_readfirstlane_b32 s16, v140
	s_cbranch_scc1 .LBB0_842
	v_lshlrev_b32_e32 v0, 4, v140
	v_add_u32_e32 v1, 0x2000, v0
	v_ashrrev_i32_e32 v2, 31, v1
	v_lshrrev_b32_e32 v2, 22, v2
	v_add_u32_e32 v2, v1, v2
	v_ashrrev_i32_e32 v8, 10, v2
	v_mul_i32_i24_e32 v2, 0x400, v8
	v_sub_u32_e32 v1, v1, v2
	v_lshrrev_b32_e32 v2, 4, v1
	v_bitop3_b32 v1, v2, v1, 32 bitop3:0x6c
	v_ashrrev_i32_e32 v2, 31, v1
	v_lshrrev_b32_e32 v2, 26, v2
	v_add_u32_e32 v2, v1, v2
	v_lshlrev_b32_e32 v3, 3, v8
	v_ashrrev_i32_e32 v9, 6, v2
	v_and_b32_e32 v3, -16, v3
	v_add_u32_e32 v3, v9, v3
	v_and_b32_e32 v4, 3, v9
	s_mov_b32 s0, 0xfffe0
	v_lshrrev_b32_e32 v5, 2, v3
	v_lshlrev_b32_e32 v6, 1, v3
	v_and_b32_e32 v2, 0xc0, v2
	v_and_or_b32 v4, v3, s0, v4
	v_and_b32_e32 v5, 4, v5
	v_and_b32_e32 v6, 24, v6
	v_sub_u32_e32 v1, v1, v2
	v_mov_b32_e32 v2, 1
	v_or3_b32 v4, v4, v5, v6
	v_lshlrev_b32_e32 v5, 5, v8
	v_ashrrev_i16_sdwa v1, v2, sext(v1) dst_sel:DWORD dst_unused:UNUSED_PAD src0_sel:DWORD src1_sel:BYTE_0
	v_and_b32_e32 v5, 32, v5
	v_bfe_i32 v10, v1, 0, 16
	v_add_lshl_u32 v1, v5, v10, 1
	v_lshl_add_u32 v128, v4, 12, v1
	v_lshl_add_u32 v130, v3, 12, v1
	v_bfe_i32 v1, v140, 27, 1
	v_lshrrev_b32_e32 v1, 22, v1
	v_add_u32_e32 v1, v0, v1
	v_and_b32_e32 v1, 0xfffffc00, v1
	v_sub_u32_e32 v0, v0, v1
	v_lshrrev_b32_e32 v1, 4, v0
	v_ashrrev_i32_e32 v3, 31, v140
	v_bitop3_b32 v0, v1, v0, 32 bitop3:0x6c
	v_lshrrev_b32_e32 v3, 26, v3
	v_ashrrev_i32_e32 v1, 31, v0
	v_add_u32_e32 v3, v140, v3
	v_lshrrev_b32_e32 v1, 26, v1
	v_ashrrev_i32_e32 v12, 6, v3
	v_add_u32_e32 v1, v0, v1
	v_lshlrev_b32_e32 v3, 3, v12
	v_ashrrev_i32_e32 v11, 6, v1
	v_and_b32_e32 v3, -16, v3
	v_add_u32_e32 v3, v11, v3
	v_and_b32_e32 v4, 3, v11
	v_and_or_b32 v4, v3, s0, v4
	s_and_b32 s98, s70, 7
	s_lshl_b32 s98, s98, 5
	s_lshr_b32 s99, s70, 3
	s_or_b32 s98, s98, s99
	s_ashr_i32 s0, s98, 2
	s_ashr_i32 s15, s16, 6
	s_ashr_i32 s1, s0, 31
	s_ashr_i32 s14, s16, 8
	s_lshl_b32 s20, s15, 10
	s_lshl_b64 s[18:19], s[0:1], 20
	v_readlane_b32 s2, v252, 38
	v_readlane_b32 s3, v252, 39
	s_add_u32 s4, s2, s18
	s_addc_u32 s5, s3, s19
	s_lshl_b32 s1, s0, 6
	s_and_b32 s21, s1, 0xfffffc00
	s_lshl_b32 s1, s98, 8
	s_and_b32 s2, s1, 0x300
	v_lshrrev_b32_e32 v5, 2, v3
	v_lshlrev_b32_e32 v6, 1, v3
	v_and_b32_e32 v1, 0xc0, v1
	s_or_b32 s6, s21, s2
	v_and_b32_e32 v5, 4, v5
	v_and_b32_e32 v6, 24, v6
	v_sub_u32_e32 v0, v0, v1
	s_ashr_i32 s7, s6, 31
	v_or3_b32 v4, v4, v5, v6
	v_lshlrev_b32_e32 v5, 5, v12
	v_ashrrev_i16_sdwa v0, v2, sext(v0) dst_sel:DWORD dst_unused:UNUSED_PAD src0_sel:DWORD src1_sel:BYTE_0
	s_lshl_b64 s[6:7], s[6:7], 12
	v_readlane_b32 s12, v252, 44
	v_and_b32_e32 v5, 32, v5
	v_bfe_i32 v13, v0, 0, 16
	v_readlane_b32 s13, v252, 45
	s_add_u32 s6, s12, s6
	v_add_lshl_u32 v0, v5, v13, 1
	s_addc_u32 s7, s13, s7
	s_add_i32 s3, s20, 0
	v_lshl_add_u32 v132, v4, 12, v0
	s_add_i32 m0, s3, 0x10000
	v_lshl_add_u32 v134, v3, 12, v0
	global_load_lds_dwordx4 v132, s[6:7]
	s_add_i32 m0, s3, 0x12000
	s_add_u32 s12, s6, 0x80000
	global_load_lds_dwordx4 v128, s[6:7]
	s_addc_u32 s13, s7, 0
	s_add_i32 m0, s3, 0x14000
	s_add_i32 s27, s3, 0x2000
	global_load_lds_dwordx4 v132, s[12:13]
	s_add_i32 m0, s3, 0x16000
	v_mov_b32_e32 v133, 0
	global_load_lds_dwordx4 v128, s[12:13]
	s_mov_b32 m0, s3
	s_add_u32 s12, s4, 0x80000
	global_load_lds_dwordx4 v134, s[4:5]
	s_mov_b32 m0, s27
	s_addc_u32 s13, s5, 0
	s_add_i32 s28, s3, 0x4000
	global_load_lds_dwordx4 v130, s[4:5]
	s_mov_b32 m0, s28
	s_add_i32 s29, s3, 0x6000
	global_load_lds_dwordx4 v134, s[12:13]
	s_mov_b32 m0, s29
	v_mov_b32_e32 v129, v133
	global_load_lds_dwordx4 v130, s[12:13]
	v_mov_b32_e32 v135, v133
	v_mov_b32_e32 v131, v133
	s_cmp_eq_u32 s14, 1
	v_lshl_add_u64 v[6:7], s[6:7], 0, v[132:133]
	v_lshl_add_u64 v[4:5], s[6:7], 0, v[128:129]
	v_lshl_add_u64 v[0:1], s[4:5], 0, v[134:135]
	s_cselect_b64 s[12:13], -1, 0
	s_cmp_lg_u32 s14, 1
	v_lshl_add_u64 v[2:3], s[4:5], 0, v[130:131]
	s_cbranch_scc1 .LBB0_797
	s_barrier

	.amdhsa_kernel _Z10fwd_kernel4Args
		.amdhsa_group_segment_fixed_size 0
		.amdhsa_private_segment_fixed_size 0
		.amdhsa_kernarg_size 440
		.amdhsa_user_sgpr_count 2
		.amdhsa_user_sgpr_dispatch_ptr 0
		.amdhsa_user_sgpr_queue_ptr 0
		.amdhsa_user_sgpr_kernarg_segment_ptr 1
		.amdhsa_user_sgpr_dispatch_id 0
		.amdhsa_user_sgpr_kernarg_preload_length 0
		.amdhsa_user_sgpr_kernarg_preload_offset 0
		.amdhsa_user_sgpr_private_segment_size 0
		.amdhsa_uses_dynamic_stack 0
		.amdhsa_enable_private_segment 0
		.amdhsa_system_sgpr_workgroup_id_x 1
		.amdhsa_system_sgpr_workgroup_id_y 0
		.amdhsa_system_sgpr_workgroup_id_z 0
		.amdhsa_system_sgpr_workgroup_info 0
		.amdhsa_system_vgpr_workitem_id 2
		.amdhsa_next_free_vgpr 253
		.amdhsa_next_free_sgpr 102
		.amdhsa_accum_offset 256
		.amdhsa_reserve_vcc 1
		.amdhsa_float_round_mode_32 0
		.amdhsa_float_round_mode_16_64 0
		.amdhsa_float_denorm_mode_32 3
		.amdhsa_float_denorm_mode_16_64 3
		.amdhsa_dx10_clamp 1
		.amdhsa_ieee_mode 1
		.amdhsa_fp16_overflow 0
		.amdhsa_tg_split 0
		.amdhsa_exception_fp_ieee_invalid_op 0
		.amdhsa_exception_fp_denorm_src 0
		.amdhsa_exception_fp_ieee_div_zero 0
		.amdhsa_exception_fp_ieee_overflow 0
		.amdhsa_exception_fp_ieee_underflow 0
		.amdhsa_exception_fp_ieee_inexact 0
		.amdhsa_exception_int_div_zero 0
	.end_amdhsa_kernel

amdhsa.kernels:
  - .agpr_count:     0
    .args:
      - .offset:         0
        .size:           184
        .value_kind:     by_value
      - .offset:         184
        .size:           4
        .value_kind:     hidden_block_count_x
      - .offset:         188
        .size:           4
        .value_kind:     hidden_block_count_y
      - .offset:         192
        .size:           4
        .value_kind:     hidden_block_count_z
      - .offset:         196
        .size:           2
        .value_kind:     hidden_group_size_x
      - .offset:         198
        .size:           2
        .value_kind:     hidden_group_size_y
      - .offset:         200
        .size:           2
        .value_kind:     hidden_group_size_z
      - .offset:         202
        .size:           2
        .value_kind:     hidden_remainder_x
      - .offset:         204
        .size:           2
        .value_kind:     hidden_remainder_y
      - .offset:         206
        .size:           2
        .value_kind:     hidden_remainder_z
      - .offset:         224
        .size:           8
        .value_kind:     hidden_global_offset_x
      - .offset:         232
        .size:           8
        .value_kind:     hidden_global_offset_y
      - .offset:         240
        .size:           8
        .value_kind:     hidden_global_offset_z
      - .offset:         248
        .size:           2
        .value_kind:     hidden_grid_dims
      - .offset:         272
        .size:           8
        .value_kind:     hidden_multigrid_sync_arg
      - .offset:         304
        .size:           4
        .value_kind:     hidden_dynamic_lds_size
    .group_segment_fixed_size: 0
    .kernarg_segment_align: 8
    .kernarg_segment_size: 440
    .language:       OpenCL C
    .language_version:
      - 2
      - 0
    .max_flat_workgroup_size: 512
    .name:           _Z10fwd_kernel4Args
    .private_segment_fixed_size: 0
    .sgpr_count:     108
    .sgpr_spill_count: 55
    .symbol:         _Z10fwd_kernel4Args.kd
    .uniform_work_group_size: 1
    .uses_dynamic_stack: false
    .vgpr_count:     253
    .vgpr_spill_count: 0
    .wavefront_size: 64
